# convert phase: bf16 weight stores marked non-temporal (nt), like its f32 loads
# baseline (speedup 1.0000x reference)
; __device__ __forceinline__ u32x4 pack8(const float* f) { u32x4 w; w.x = cvt_pk_bf16(f[0], f[1]); w.y = cvt_pk_bf16(f[2], f[3]); w.z = cvt_pk_bf16(f[4], f[5]); w.w = cvt_pk_bf16(f[6], f[7]); return w; }
; __device__ __forceinline__ void convert_phase(const Params& p, LAS unsigned char* lds) {
;     ...
;         for (int i = 0; i < 4; ++i) { const int ch = tid + 512 * i, n = ch >> 3, k8 = (ch & 7) * 8, gn = cur.nt * 256 + n;
;             if (gn < cur.N) { float f[8];
; #pragma unroll
;                 for (int j = 0; j < 8; ++j) f[j] = T[(k8 + j) * 257 + n];
;                 *(u32x4*)(cur.dst + (size_t)map_col(gn, cur.mode) * cur.K + cur.kt * 64 + k8) = pack8(f); } }
.Lcv_nogk_0:
	s_waitcnt lgkmcnt(0)
	v_cvt_pk_bf16_f32 v152, v120, v121
	v_cvt_pk_bf16_f32 v153, v122, v123
	v_cvt_pk_bf16_f32 v154, v124, v125
	v_cvt_pk_bf16_f32 v155, v126, v127
	global_store_dwordx4 v177, v[152:155], s[64:65] nt
	s_nop 1
	v_cvt_pk_bf16_f32 v152, v128, v129
	v_cvt_pk_bf16_f32 v153, v130, v131
	v_cvt_pk_bf16_f32 v154, v132, v133
	v_cvt_pk_bf16_f32 v155, v134, v135
	global_store_dwordx4 v178, v[152:155], s[64:65] nt
	s_nop 1
	v_cvt_pk_bf16_f32 v152, v136, v137
	v_cvt_pk_bf16_f32 v153, v138, v139
	v_cvt_pk_bf16_f32 v154, v140, v141
	v_cvt_pk_bf16_f32 v155, v142, v143
	global_store_dwordx4 v179, v[152:155], s[64:65] nt
	s_nop 1
	v_cvt_pk_bf16_f32 v152, v144, v145
	v_cvt_pk_bf16_f32 v153, v146, v147
	v_cvt_pk_bf16_f32 v154, v148, v149
	v_cvt_pk_bf16_f32 v155, v150, v151
	global_store_dwordx4 v180, v[152:155], s[64:65] nt
	s_cmp_eq_u32 s29, 0
	s_cbranch_scc0 .Lcv_nog_0
	global_load_dwordx4 v[96:99], v164, s[38:39]
	global_load_dwordx4 v[100:103], v164, s[38:39] offset:16
	s_mov_b32 s64, s40
	s_mov_b32 s65, s41
	s_mov_b32 s66, s42
	s_mov_b32 s67, s43
	s_mov_b32 s68, s44
	s_mov_b32 s69, s45
	s_mov_b32 s70, s46

; __device__ __forceinline__ u32x4 pack8(const float* f) { u32x4 w; w.x = cvt_pk_bf16(f[0], f[1]); w.y = cvt_pk_bf16(f[2], f[3]); w.z = cvt_pk_bf16(f[4], f[5]); w.w = cvt_pk_bf16(f[6], f[7]); return w; }
; __device__ __forceinline__ void convert_phase(const Params& p, LAS unsigned char* lds) {
;     ...
;         for (int i = 0; i < 4; ++i) { const int ch = tid + 512 * i, n = ch >> 3, k8 = (ch & 7) * 8, gn = cur.nt * 256 + n;
;             if (gn < cur.N) { float f[8];
; #pragma unroll
;                 for (int j = 0; j < 8; ++j) f[j] = T[(k8 + j) * 257 + n];
;                 *(u32x4*)(cur.dst + (size_t)map_col(gn, cur.mode) * cur.K + cur.kt * 64 + k8) = pack8(f); } }
.Lcv_nogk_1:
	s_waitcnt lgkmcnt(0)
	v_cvt_pk_bf16_f32 v152, v120, v121
	v_cvt_pk_bf16_f32 v153, v122, v123
	v_cvt_pk_bf16_f32 v154, v124, v125
	v_cvt_pk_bf16_f32 v155, v126, v127
	global_store_dwordx4 v177, v[152:155], s[72:73] nt
	s_nop 1
	v_cvt_pk_bf16_f32 v152, v128, v129
	v_cvt_pk_bf16_f32 v153, v130, v131
	v_cvt_pk_bf16_f32 v154, v132, v133
	v_cvt_pk_bf16_f32 v155, v134, v135
	global_store_dwordx4 v178, v[152:155], s[72:73] nt
	s_nop 1
	v_cvt_pk_bf16_f32 v152, v136, v137
	v_cvt_pk_bf16_f32 v153, v138, v139
	v_cvt_pk_bf16_f32 v154, v140, v141
	v_cvt_pk_bf16_f32 v155, v142, v143
	global_store_dwordx4 v179, v[152:155], s[72:73] nt
	s_nop 1
	v_cvt_pk_bf16_f32 v152, v144, v145
	v_cvt_pk_bf16_f32 v153, v146, v147
	v_cvt_pk_bf16_f32 v154, v148, v149
	v_cvt_pk_bf16_f32 v155, v150, v151
	global_store_dwordx4 v180, v[152:155], s[72:73] nt
	s_cmp_eq_u32 s29, 0
	s_cbranch_scc0 .Lcv_nog_1
	global_load_dwordx4 v[104:107], v164, s[38:39]
	global_load_dwordx4 v[108:111], v164, s[38:39] offset:16
	s_mov_b32 s72, s40
	s_mov_b32 s73, s41
	s_mov_b32 s74, s42
	s_mov_b32 s75, s43
	s_mov_b32 s76, s44
	s_mov_b32 s77, s45
	s_mov_b32 s78, s46

; __device__ __forceinline__ u32x4 pack8(const float* f) { u32x4 w; w.x = cvt_pk_bf16(f[0], f[1]); w.y = cvt_pk_bf16(f[2], f[3]); w.z = cvt_pk_bf16(f[4], f[5]); w.w = cvt_pk_bf16(f[6], f[7]); return w; }
; __device__ __forceinline__ void convert_phase(const Params& p, LAS unsigned char* lds) {
;     ...
;         for (int i = 0; i < 4; ++i) { const int ch = tid + 512 * i, n = ch >> 3, k8 = (ch & 7) * 8, gn = cur.nt * 256 + n;
;             if (gn < cur.N) { float f[8];
; #pragma unroll
;                 for (int j = 0; j < 8; ++j) f[j] = T[(k8 + j) * 257 + n];
;                 *(u32x4*)(cur.dst + (size_t)map_col(gn, cur.mode) * cur.K + cur.kt * 64 + k8) = pack8(f); } }
.Lcv_nogk_2:
	s_waitcnt lgkmcnt(0)
	v_cvt_pk_bf16_f32 v152, v120, v121
	v_cvt_pk_bf16_f32 v153, v122, v123
	v_cvt_pk_bf16_f32 v154, v124, v125
	v_cvt_pk_bf16_f32 v155, v126, v127
	global_store_dwordx4 v177, v[152:155], s[48:49] nt
	s_nop 1
	v_cvt_pk_bf16_f32 v152, v128, v129
	v_cvt_pk_bf16_f32 v153, v130, v131
	v_cvt_pk_bf16_f32 v154, v132, v133
	v_cvt_pk_bf16_f32 v155, v134, v135
	global_store_dwordx4 v178, v[152:155], s[48:49] nt
	s_nop 1
	v_cvt_pk_bf16_f32 v152, v136, v137
	v_cvt_pk_bf16_f32 v153, v138, v139
	v_cvt_pk_bf16_f32 v154, v140, v141
	v_cvt_pk_bf16_f32 v155, v142, v143
	global_store_dwordx4 v179, v[152:155], s[48:49] nt
	s_nop 1
	v_cvt_pk_bf16_f32 v152, v144, v145
	v_cvt_pk_bf16_f32 v153, v146, v147
	v_cvt_pk_bf16_f32 v154, v148, v149
	v_cvt_pk_bf16_f32 v155, v150, v151
	global_store_dwordx4 v180, v[152:155], s[48:49] nt
	s_cmp_eq_u32 s29, 0
	s_cbranch_scc0 .Lcv_nog_2
	global_load_dwordx4 v[112:115], v164, s[38:39]
	global_load_dwordx4 v[116:119], v164, s[38:39] offset:16
	s_mov_b32 s48, s40
	s_mov_b32 s49, s41
	s_mov_b32 s50, s42
	s_mov_b32 s51, s43
	s_mov_b32 s52, s44
	s_mov_b32 s47, s45
	s_mov_b32 s33, s46
